# v54 + pipelined seam polling: 4 polls of the per-XCC release word in flight (one new poll per returned one) instead of one blocking poll per iteration
# baseline (speedup 1.0000x reference)
; __device__ __forceinline__ unsigned xb_ld(unsigned* p)              { return __hip_atomic_load(p, __ATOMIC_RELAXED, __HIP_MEMORY_SCOPE_AGENT); }
; #define XB_SPIN(cond, bar) do { unsigned _sp = 0; while (cond) { __builtin_amdgcn_s_sleep(1); \
;     if ((++_sp & 255u) == 0u) { if (xb_ld(&(bar)[XB_TMO])) break; if (_sp > XB_SPIN_CAP) { atomicAdd(&(bar)[XB_TMO], 1u); break; } } } } while (0)
; __device__ __forceinline__ void xcd_barrier(const XcdBarrier& b) {
;     ...
;             XB_SPIN(xb_ld(&bar[XB_XGEN(b.x)]) == gen, bar);
.Lxb_wait_0:
	v_mov_b32_e32 v3, 0x2400
	s_mov_b32 s14, 0
	global_load_dword v252, v3, s[38:39] sc1
	s_sleep 5
	global_load_dword v253, v3, s[38:39] sc1
	s_sleep 5
	global_load_dword v254, v3, s[38:39] sc1
.Lxb_spin_0:
	s_sleep 5
	global_load_dword v255, v3, s[38:39] sc1
	s_waitcnt vmcnt(3)
	v_cmp_ne_u32_e32 vcc, v252, v1
	s_cbranch_vccnz .Lxb_out_0
	s_sleep 5
	global_load_dword v252, v3, s[38:39] sc1
	s_waitcnt vmcnt(3)
	v_cmp_ne_u32_e32 vcc, v253, v1
	s_cbranch_vccnz .Lxb_out_0
	s_sleep 5
	global_load_dword v253, v3, s[38:39] sc1
	s_waitcnt vmcnt(3)
	v_cmp_ne_u32_e32 vcc, v254, v1
	s_cbranch_vccnz .Lxb_out_0
	s_sleep 5
	global_load_dword v254, v3, s[38:39] sc1
	s_waitcnt vmcnt(3)
	v_cmp_ne_u32_e32 vcc, v255, v1
	s_cbranch_vccnz .Lxb_out_0
	s_add_i32 s14, s14, 1
	s_and_b32 s15, s14, 0x3f
	s_cmp_lg_u32 s15, 0
	s_cbranch_scc1 .Lxb_spin_0
	global_load_dword v5, v10, s[40:41] sc1
	s_waitcnt vmcnt(0)
	v_cmp_ne_u32_e32 vcc, 0, v5
	s_cbranch_vccnz .Lxb_out_0
	s_cmp_lt_u32 s14, 0x10001
	s_cbranch_scc1 .Lxb_spin_0
	global_atomic_add v10, v4, s[40:41]
